# l0_prep statistics loop: wave sums via DPP row reduction plus v_readlane instead of six ds_bpermute round trips
# speedup vs baseline: 1.0066x; 1.0005x over previous
; DI float bflo(unsigned u) { return __uint_as_float(u << 16); }
; DI float bfhi(unsigned u) { return __uint_as_float(u & 0xffff0000u); }
; DI void phase_l0_prep(int wv, const ArgP a) {
;     ...
;         const bf16_t* zr = Z + (size_t)t * 1536;
;         float sq = 0.f, skv = 0.f;
;         { const u32x2 v = *(const u32x2*)(zr + 1024 + lane * 4); const float p0 = bflo(v.x), p1 = bfhi(v.x), p2 = bflo(v.y), p3 = bfhi(v.y); sq = p0 * p0 + p1 * p1 + p2 * p2 + p3 * p3; }
;         { const unsigned v = *(const unsigned*)(zr + 1280 + lane * 2); const float p0 = bflo(v), p1 = bfhi(v); skv = p0 * p0 + p1 * p1; }
;         sq = wave_sum(sq); skv = wave_sum(skv);
;         if (lane == 0) { rsq[t] = rsqrtf(sq * (1.f / 256.f) + EPS); rskv[t] = rsqrtf(skv * (1.f / 128.f) + EPS); }
.LBB0_465:
	v_mad_i64_i32 v[16:17], s[8:9], v0, s21, v[6:7]
	v_lshl_add_u64 v[18:19], v[16:17], 0, v[8:9]
	global_load_dwordx2 v[18:19], v[18:19], off offset:2048
	s_waitcnt lgkmcnt(0)
	v_lshl_add_u64 v[20:21], v[16:17], 0, v[12:13]
	global_load_dword v1, v[20:21], off offset:2560
	v_mov_b32_e32 v44, v0
	v_ashrrev_i32_e32 v45, 31, v0
	v_lshl_add_u64 v[46:47], v[16:17], 0, v[2:3]
	v_lshlrev_b64 v[44:45], 7, v[44:45]
	v_lshl_add_u64 v[44:45], v[4:5], 0, v[44:45]
	s_and_saveexec_b64 s[18:19], s[6:7]
	global_load_ushort v40, v[46:47], off offset:2816
	global_load_ushort v41, v[46:47], off offset:2848
	global_load_dwordx2 v[42:43], v[44:45], off
	s_or_b64 exec, exec, s[18:19]
	s_waitcnt vmcnt(4)
	v_and_b32_e32 v11, 0xffff0000, v18
	v_and_b32_e32 v21, 0xffff0000, v19
	v_lshlrev_b32_e32 v19, 16, v19
	v_lshlrev_b32_e32 v18, 16, v18
	s_waitcnt vmcnt(3)
	v_lshlrev_b32_e32 v20, 16, v1
	v_and_b32_e32 v1, 0xffff0000, v1
	v_pk_mul_f32 v[18:19], v[18:19], v[18:19]
	v_mul_f32_e32 v22, v1, v1
	v_fma_f32 v1, v11, v11, v18
	v_add_f32_e32 v23, v19, v1
	v_pk_fma_f32 v[18:19], v[20:21], v[20:21], v[22:23]
	v_ashrrev_i32_e32 v1, 31, v0
	s_nop 1
	v_add_f32_dpp v18, v18, v18 quad_perm:[1,0,3,2] row_mask:0xf bank_mask:0xf
	v_add_f32_dpp v19, v19, v19 quad_perm:[1,0,3,2] row_mask:0xf bank_mask:0xf
	s_nop 1
	v_add_f32_dpp v18, v18, v18 quad_perm:[2,3,0,1] row_mask:0xf bank_mask:0xf
	v_add_f32_dpp v19, v19, v19 quad_perm:[2,3,0,1] row_mask:0xf bank_mask:0xf
	s_nop 1
	v_add_f32_dpp v18, v18, v18 row_half_mirror row_mask:0xf bank_mask:0xf
	v_add_f32_dpp v19, v19, v19 row_half_mirror row_mask:0xf bank_mask:0xf
	s_nop 1
	v_add_f32_dpp v18, v18, v18 row_mirror row_mask:0xf bank_mask:0xf
	v_add_f32_dpp v19, v19, v19 row_mirror row_mask:0xf bank_mask:0xf
	s_nop 1
	v_readlane_b32 s29, v18, 16
	v_readlane_b32 s30, v19, 16
	v_readlane_b32 s31, v18, 32
	v_readlane_b32 s32, v19, 32
	v_readlane_b32 s33, v18, 48
	v_readlane_b32 s34, v19, 48
	s_nop 1
	v_add_f32_e32 v18, s29, v18
	v_add_f32_e32 v19, s30, v19
	v_add_f32_e32 v18, s31, v18
	v_add_f32_e32 v19, s32, v19
	v_add_f32_e32 v18, s33, v18
	v_add_f32_e32 v19, s34, v19
	s_and_saveexec_b64 s[18:19], s[4:5]
	s_cbranch_execz .LBB0_467
	v_lshlrev_b64 v[22:23], 2, v[0:1]
	v_pk_fma_f32 v[18:19], v[18:19], s[2:3], v[14:15] op_sel_hi:[1,1,0]
	v_lshl_add_u64 v[24:25], s[12:13], 0, v[22:23]
	v_mul_f32_e32 v11, 0x4b800000, v19
	v_cmp_gt_f32_e32 vcc, s22, v19
	v_mul_f32_e32 v15, 0x4b800000, v18
	v_cmp_gt_f32_e64 s[8:9], s22, v18
	v_cndmask_b32_e32 v11, v19, v11, vcc
	v_rsq_f32_e32 v11, v11
	v_cndmask_b32_e64 v15, v18, v15, s[8:9]
	v_rsq_f32_e32 v15, v15
	v_mul_f32_e32 v18, 0x45800000, v11
	v_cndmask_b32_e32 v11, v11, v18, vcc
	global_store_dword v[24:25], v11, off
	v_mul_f32_e32 v11, 0x45800000, v15
	v_cndmask_b32_e64 v11, v15, v11, s[8:9]
	v_lshl_add_u64 v[18:19], s[14:15], 0, v[22:23]
	global_store_dword v[18:19], v11, off
